# Fourier stage 1: wave roles rotated so each SIMD holds one storing wave and one mostly-idle wave (balances VALU/store issue across SIMDs)
# baseline (speedup 1.0000x reference)
.LBB0_738:
	s_cmp_lt_i32 s58, 10
	s_cselect_b64 s[24:25], -1, 0
	s_cmp_gt_i32 s58, 9
	s_cselect_b64 s[0:1], -1, 0
	s_cmp_lt_i32 s59, 10
	s_cselect_b64 s[4:5], -1, 0
	s_or_b64 s[0:1], s[0:1], s[4:5]
	s_and_b64 vcc, exec, s[0:1]
	s_cbranch_vccnz .LBB0_768
	s_waitcnt vmcnt(0)
	v_and_b32_e32 v2, 0x3ff, v0
	v_lshrrev_b32_e32 v3, 1, v2
	v_and_b32_e32 v3, 0xc0, v3
	v_and_b32_e32 v4, 64, v2
	v_and_b32_e32 v2, 63, v2
	v_lshl_or_b32 v2, v4, 2, v2
	v_or_b32_e32 v2, v2, v3
	s_waitcnt lgkmcnt(0)
	v_cvt_f32_u32_e32 v3, v2
	v_or_b32_e32 v4, 0x200, v2
	v_cvt_f32_u32_e32 v4, v4
	v_or_b32_e32 v6, 0x400, v2
	v_mul_f32_e32 v3, 0x39800000, v3
	v_cos_f32_e32 v5, v3
	v_mul_f32_e32 v3, 0x39800000, v4
	v_cos_f32_e32 v4, v3
	v_cvt_f32_u32_e32 v7, v6
	s_add_i32 s8, 0, 0x10000
	v_lshl_add_u32 v3, v2, 2, s8
	ds_write2st64_b32 v3, v5, v4 offset1:8
	v_mul_f32_e32 v4, 0x39800000, v7
	v_lshl_add_u32 v5, v6, 2, s8
	v_or_b32_e32 v6, 0x600, v2
	v_or_b32_e32 v7, 0x800, v2
	v_cos_f32_e32 v4, v4
	v_cvt_f32_u32_e32 v6, v6
	v_cvt_f32_u32_e32 v8, v7
	v_lshl_add_u32 v7, v7, 2, s8
	ds_write_b32 v5, v4
	v_mul_f32_e32 v4, 0x39800000, v6
	v_mul_f32_e32 v5, 0x39800000, v8
	v_or_b32_e32 v6, 0xa00, v2
	v_or_b32_e32 v8, 0xc00, v2
	v_cvt_f32_u32_e32 v6, v6
	v_cvt_f32_u32_e32 v9, v8
	v_cos_f32_e32 v5, v5
	v_cos_f32_e32 v4, v4
	v_mul_f32_e32 v6, 0x39800000, v6
	v_mul_f32_e32 v9, 0x39800000, v9
	v_cos_f32_e32 v6, v6
	v_cos_f32_e32 v9, v9
	s_movk_i32 s0, 0xe00
	ds_write_b32 v7, v5
	ds_write2st64_b32 v3, v4, v6 offset0:24 offset1:40
	v_lshl_add_u32 v4, v8, 2, s8
	v_cmp_gt_u32_e32 vcc, s0, v8
	ds_write_b32 v4, v9
	s_and_saveexec_b64 s[0:1], vcc
	s_cbranch_execz .LBB0_741
	v_add_u32_e32 v4, 0xe00, v2
	v_cvt_f32_u32_e32 v4, v4
	v_mul_f32_e32 v4, 0x39800000, v4
	v_cos_f32_e32 v4, v4
	ds_write_b32 v3, v4 offset:14336
